# attention: non-diag key tiles use hand-scheduled path with LDS operand prefetch and exp/cvt interleaved with PV MFMAs
# speedup vs baseline: 1.0017x; 1.0017x over previous
.LBB0_589:
	s_bitcmp1_b32 s70, 0
	v_cvt_f32_i32_e32 v130, v190
	s_cselect_b32 s1, 0x8200, 0
	s_addk_i32 s1, 0x100
	s_cmp_eq_u32 s4, s70
	s_cbranch_scc1 .Latt_diag
	v_add_u32_e32 v127, s1, v166
	ds_read_b128 v[198:201], v127
	ds_read_b128 v[222:225], v186
	ds_read_b128 v[202:205], v127 offset:2080
	ds_read_b128 v[226:229], v186 offset:4128
	ds_read_b128 v[206:209], v127 offset:4160
	ds_read_b128 v[230:233], v186 offset:8256
	ds_read_b128 v[210:213], v127 offset:6240
	ds_read_b128 v[234:237], v186 offset:12384
	ds_read_b128 v[214:217], v127 offset:512
	ds_read_b128 v[218:221], v127 offset:2592
	v_fma_f32 v192, -v129, v130, -v188
	v_mov_b32_e32 v80, v129
	v_add3_u32 v191, s1, v167, v168
	v_fma_f32 v64, 0, v80, v192
	v_add_f32_e32 v65, v80, v192
	v_pk_fma_f32 v[66:67], v[80:81], s[84:85], v[192:193] op_sel_hi:[0,1,0]
	v_pk_fma_f32 v[68:69], v[80:81], s[86:87], v[192:193] op_sel_hi:[0,1,0]
	v_pk_fma_f32 v[70:71], v[80:81], s[88:89], v[192:193] op_sel_hi:[0,1,0]
	v_pk_fma_f32 v[72:73], v[80:81], s[90:91], v[192:193] op_sel_hi:[0,1,0]
	v_pk_fma_f32 v[74:75], v[80:81], s[92:93], v[192:193] op_sel_hi:[0,1,0]
	v_pk_fma_f32 v[76:77], v[80:81], s[94:95], v[192:193] op_sel_hi:[0,1,0]
	v_pk_fma_f32 v[78:79], v[80:81], s[96:97], v[192:193] op_sel_hi:[0,1,0]
	v_pk_fma_f32 v[94:95], v[80:81], s[22:23], v[192:193] op_sel_hi:[0,1,0]
	v_pk_fma_f32 v[92:93], v[80:81], s[74:75], v[192:193] op_sel_hi:[0,1,0]
	v_pk_fma_f32 v[90:91], v[80:81], s[76:77], v[192:193] op_sel_hi:[0,1,0]
	v_pk_fma_f32 v[88:89], v[80:81], s[24:25], v[192:193] op_sel_hi:[0,1,0]
	v_pk_fma_f32 v[86:87], v[80:81], s[26:27], v[192:193] op_sel_hi:[0,1,0]
	v_pk_fma_f32 v[84:85], v[80:81], s[72:73], v[192:193] op_sel_hi:[0,1,0]
	v_pk_fma_f32 v[82:83], v[80:81], s[18:19], v[192:193] op_sel_hi:[0,1,0]
	v_pk_fma_f32 v[80:81], v[80:81], s[34:35], v[192:193] op_sel_hi:[0,1,0]
	ds_read_b128 v[192:195], v127 offset:4672
	s_waitcnt lgkmcnt(9)
	v_mfma_f32_32x32x16_bf16 v[64:79], v[198:201], v[222:225], v[64:79]
	ds_read_b128 v[198:201], v127 offset:6752
	s_waitcnt lgkmcnt(8)
	v_mfma_f32_32x32x16_bf16 v[64:79], v[202:205], v[226:229], v[64:79]
	s_waitcnt lgkmcnt(6)
	v_mfma_f32_32x32x16_bf16 v[64:79], v[206:209], v[230:233], v[64:79]
	s_waitcnt lgkmcnt(4)
	v_mfma_f32_32x32x16_bf16 v[64:79], v[210:213], v[234:237], v[64:79]
	ds_read_b128 v[202:205], v191 offset:16640
	ds_read_b128 v[206:209], v191 offset:17152
	ds_read_b128 v[210:213], v191 offset:17664
	s_waitcnt lgkmcnt(6)
	v_mfma_f32_32x32x16_bf16 v[80:95], v[214:217], v[222:225], v[80:95]
	s_waitcnt lgkmcnt(5)
	v_mfma_f32_32x32x16_bf16 v[80:95], v[218:221], v[226:229], v[80:95]
	s_waitcnt lgkmcnt(4)
	v_mfma_f32_32x32x16_bf16 v[80:95], v[192:195], v[230:233], v[80:95]
	s_waitcnt lgkmcnt(3)
	v_mfma_f32_32x32x16_bf16 v[80:95], v[198:201], v[234:237], v[80:95]
	ds_read_b128 v[214:217], v191 offset:18176
	ds_read_b128 v[218:221], v191 offset:20768
	ds_read_b128 v[192:195], v191 offset:21280
	ds_read_b128 v[198:201], v191 offset:21792
	ds_read_b128 v[222:225], v191 offset:22304
	ds_read_b128 v[226:229], v191 offset:24896
	ds_read_b128 v[230:233], v191 offset:25408
	ds_read_b128 v[234:237], v191 offset:25920
	v_exp_f32_e32 v64, v64
	v_exp_f32_e32 v65, v65
	v_exp_f32_e32 v66, v66
	v_exp_f32_e32 v67, v67
	v_exp_f32_e32 v68, v68
	v_exp_f32_e32 v69, v69
	v_exp_f32_e32 v70, v70
	v_exp_f32_e32 v71, v71
	v_add_f32_e32 v130, v64, v65
	v_add_f32_e32 v130, v130, v66
	v_add_f32_e32 v130, v130, v67
	v_add_f32_e32 v130, v130, v68
	v_add_f32_e32 v130, v130, v69
	v_add_f32_e32 v130, v130, v70
	v_add_f32_e32 v130, v130, v71
	v_cvt_pk_bf16_f32 v64, v64, v65
	v_cvt_pk_bf16_f32 v65, v66, v67
	v_cvt_pk_bf16_f32 v66, v68, v69
	v_cvt_pk_bf16_f32 v67, v70, v71
	s_waitcnt lgkmcnt(10)
	v_exp_f32_e32 v72, v72
	v_mfma_f32_32x32x16_bf16 v[48:63], v[202:205], v[64:67], v[48:63]
	v_exp_f32_e32 v73, v73
	v_exp_f32_e32 v74, v74
	v_add_f32_e32 v130, v130, v72
	v_add_f32_e32 v130, v130, v73
	s_waitcnt lgkmcnt(9)
	v_mfma_f32_32x32x16_bf16 v[32:47], v[206:209], v[64:67], v[32:47]
	v_exp_f32_e32 v75, v75
	v_exp_f32_e32 v76, v76
	v_cvt_pk_bf16_f32 v68, v72, v73
	v_add_f32_e32 v130, v130, v74
	s_waitcnt lgkmcnt(8)
	v_mfma_f32_32x32x16_bf16 v[16:31], v[210:213], v[64:67], v[16:31]
	v_exp_f32_e32 v77, v77
	v_exp_f32_e32 v78, v78
	v_cvt_pk_bf16_f32 v69, v74, v75
	v_add_f32_e32 v130, v130, v75
	v_add_f32_e32 v130, v130, v76
	s_waitcnt lgkmcnt(7)
	v_mfma_f32_32x32x16_bf16 v[0:15], v[214:217], v[64:67], v[0:15]
	ds_read_b128 v[202:205], v191 offset:26432
	ds_read_b128 v[206:209], v191 offset:29024
	ds_read_b128 v[210:213], v191 offset:29536
	ds_read_b128 v[214:217], v191 offset:30048
	v_exp_f32_e32 v79, v79
	v_cvt_pk_bf16_f32 v70, v76, v77
	v_add_f32_e32 v130, v130, v77
	v_add_f32_e32 v130, v130, v78
	v_add_f32_e32 v130, v130, v79
	v_cvt_pk_bf16_f32 v71, v78, v79
	s_waitcnt lgkmcnt(10)
	v_exp_f32_e32 v80, v80
	v_mfma_f32_32x32x16_bf16 v[48:63], v[218:221], v[68:71], v[48:63]
	v_exp_f32_e32 v81, v81
	v_exp_f32_e32 v82, v82
	v_add_f32_e32 v130, v130, v80
	v_add_f32_e32 v130, v130, v81
	s_waitcnt lgkmcnt(9)
	v_mfma_f32_32x32x16_bf16 v[32:47], v[192:195], v[68:71], v[32:47]
	v_exp_f32_e32 v83, v83
	v_exp_f32_e32 v84, v84
	v_cvt_pk_bf16_f32 v72, v80, v81
	v_add_f32_e32 v130, v130, v82
	s_waitcnt lgkmcnt(8)
	v_mfma_f32_32x32x16_bf16 v[16:31], v[198:201], v[68:71], v[16:31]
	v_exp_f32_e32 v85, v85
	v_exp_f32_e32 v86, v86
	v_cvt_pk_bf16_f32 v73, v82, v83
	v_add_f32_e32 v130, v130, v83
	v_add_f32_e32 v130, v130, v84
	s_waitcnt lgkmcnt(7)
	v_mfma_f32_32x32x16_bf16 v[0:15], v[222:225], v[68:71], v[0:15]
	ds_read_b128 v[218:221], v191 offset:30560
	v_exp_f32_e32 v87, v87
	v_cvt_pk_bf16_f32 v74, v84, v85
	v_add_f32_e32 v130, v130, v85
	v_add_f32_e32 v130, v130, v86
	v_add_f32_e32 v130, v130, v87
	v_cvt_pk_bf16_f32 v75, v86, v87
	s_waitcnt lgkmcnt(7)
	v_exp_f32_e32 v88, v88
	v_mfma_f32_32x32x16_bf16 v[48:63], v[226:229], v[72:75], v[48:63]
	v_exp_f32_e32 v89, v89
	v_exp_f32_e32 v90, v90
	v_add_f32_e32 v130, v130, v88
	v_add_f32_e32 v130, v130, v89
	s_waitcnt lgkmcnt(6)
	v_mfma_f32_32x32x16_bf16 v[32:47], v[230:233], v[72:75], v[32:47]
	v_exp_f32_e32 v91, v91
	v_exp_f32_e32 v92, v92
	v_cvt_pk_bf16_f32 v76, v88, v89
	v_add_f32_e32 v130, v130, v90
	s_waitcnt lgkmcnt(5)
	v_mfma_f32_32x32x16_bf16 v[16:31], v[234:237], v[72:75], v[16:31]
	v_exp_f32_e32 v93, v93
	v_exp_f32_e32 v94, v94
	v_cvt_pk_bf16_f32 v77, v90, v91
	v_add_f32_e32 v130, v130, v91
	v_add_f32_e32 v130, v130, v92
	s_waitcnt lgkmcnt(4)
	v_mfma_f32_32x32x16_bf16 v[0:15], v[202:205], v[72:75], v[0:15]
	v_exp_f32_e32 v95, v95
	v_cvt_pk_bf16_f32 v78, v92, v93
	v_add_f32_e32 v130, v130, v93
	v_add_f32_e32 v130, v130, v94
	v_add_f32_e32 v130, v130, v95
	v_cvt_pk_bf16_f32 v79, v94, v95
	s_waitcnt lgkmcnt(3)
	s_nop 0
	v_mfma_f32_32x32x16_bf16 v[48:63], v[206:209], v[76:79], v[48:63]
	s_waitcnt lgkmcnt(2)
	v_mfma_f32_32x32x16_bf16 v[32:47], v[210:213], v[76:79], v[32:47]
	s_waitcnt lgkmcnt(1)
	v_mfma_f32_32x32x16_bf16 v[16:31], v[214:217], v[76:79], v[16:31]
	s_waitcnt lgkmcnt(0)
	v_mfma_f32_32x32x16_bf16 v[0:15], v[218:221], v[76:79], v[0:15]
	v_add_f32_e32 v150, v150, v130
	s_branch .Latt_join
.Latt_diag:
	s_cselect_b64 vcc, -1, 0
	v_fma_f32 v64, -v129, v130, -v188
	v_cndmask_b32_e64 v80, v129, 0, vcc
	v_cndmask_b32_e32 v192, v64, v189, vcc
	v_add_u32_e32 v127, s1, v166
	v_fma_f32 v64, 0, v80, v192
	v_add_f32_e32 v65, v80, v192
	v_pk_fma_f32 v[66:67], v[80:81], s[84:85], v[192:193] op_sel_hi:[0,1,0]
	v_pk_fma_f32 v[68:69], v[80:81], s[86:87], v[192:193] op_sel_hi:[0,1,0]
	v_pk_fma_f32 v[70:71], v[80:81], s[88:89], v[192:193] op_sel_hi:[0,1,0]
	v_pk_fma_f32 v[72:73], v[80:81], s[90:91], v[192:193] op_sel_hi:[0,1,0]
	v_pk_fma_f32 v[74:75], v[80:81], s[92:93], v[192:193] op_sel_hi:[0,1,0]
	v_pk_fma_f32 v[76:77], v[80:81], s[94:95], v[192:193] op_sel_hi:[0,1,0]
	v_pk_fma_f32 v[78:79], v[80:81], s[96:97], v[192:193] op_sel_hi:[0,1,0]
	v_pk_fma_f32 v[94:95], v[80:81], s[22:23], v[192:193] op_sel_hi:[0,1,0]
	v_pk_fma_f32 v[92:93], v[80:81], s[74:75], v[192:193] op_sel_hi:[0,1,0]
	v_pk_fma_f32 v[90:91], v[80:81], s[76:77], v[192:193] op_sel_hi:[0,1,0]
	v_pk_fma_f32 v[88:89], v[80:81], s[24:25], v[192:193] op_sel_hi:[0,1,0]
	v_pk_fma_f32 v[86:87], v[80:81], s[26:27], v[192:193] op_sel_hi:[0,1,0]
	v_pk_fma_f32 v[84:85], v[80:81], s[72:73], v[192:193] op_sel_hi:[0,1,0]
	v_pk_fma_f32 v[82:83], v[80:81], s[18:19], v[192:193] op_sel_hi:[0,1,0]
	v_pk_fma_f32 v[80:81], v[80:81], s[34:35], v[192:193] op_sel_hi:[0,1,0]
	ds_read_b128 v[192:195], v127
	ds_read_b128 v[198:201], v127 offset:512
	ds_read_b128 v[202:205], v186
	s_waitcnt lgkmcnt(0)
	v_mfma_f32_32x32x16_bf16 v[64:79], v[192:195], v[202:205], v[64:79]
	s_cmp_lg_u32 s4, s70
	v_mfma_f32_32x32x16_bf16 v[80:95], v[198:201], v[202:205], v[80:95]
	ds_read_b128 v[192:195], v127 offset:2080
	ds_read_b128 v[198:201], v127 offset:2592
	ds_read_b128 v[202:205], v186 offset:4128
	s_waitcnt lgkmcnt(0)
	v_mfma_f32_32x32x16_bf16 v[64:79], v[192:195], v[202:205], v[64:79]
	v_mfma_f32_32x32x16_bf16 v[80:95], v[198:201], v[202:205], v[80:95]
	ds_read_b128 v[192:195], v127 offset:4160
	ds_read_b128 v[198:201], v127 offset:4672
	ds_read_b128 v[202:205], v186 offset:8256
	s_waitcnt lgkmcnt(0)
	v_mfma_f32_32x32x16_bf16 v[64:79], v[192:195], v[202:205], v[64:79]
	v_mfma_f32_32x32x16_bf16 v[80:95], v[198:201], v[202:205], v[80:95]
	ds_read_b128 v[192:195], v127 offset:6240
	ds_read_b128 v[198:201], v127 offset:6752
	ds_read_b128 v[202:205], v186 offset:12384
	s_waitcnt lgkmcnt(0)
	v_mfma_f32_32x32x16_bf16 v[64:79], v[192:195], v[202:205], v[64:79]
	v_mfma_f32_32x32x16_bf16 v[80:95], v[198:201], v[202:205], v[80:95]
	s_cbranch_scc1 .LBB0_591
	v_add_f32_e32 v127, -1.0, v130
	v_pk_add_f32 v[192:193], v[130:131], s[42:43] op_sel_hi:[0,1]
	v_pk_add_f32 v[194:195], v[130:131], s[46:47] op_sel_hi:[0,1]
	v_pk_add_f32 v[198:199], v[130:131], s[50:51] op_sel_hi:[0,1]
	v_pk_add_f32 v[200:201], v[130:131], s[54:55] op_sel_hi:[0,1]
	v_pk_add_f32 v[202:203], v[130:131], s[58:59] op_sel_hi:[0,1]
	v_pk_add_f32 v[204:205], v[130:131], s[62:63] op_sel_hi:[0,1]
	v_pk_add_f32 v[206:207], v[130:131], s[66:67] op_sel_hi:[0,1]
	v_and_b32_e32 v193, 0x7fffffff, v193
	v_and_b32_e32 v192, 0x7fffffff, v192
	v_and_b32_e32 v195, 0x7fffffff, v195
	v_and_b32_e32 v194, 0x7fffffff, v194
	v_and_b32_e32 v199, 0x7fffffff, v199
	v_and_b32_e32 v198, 0x7fffffff, v198
	v_and_b32_e32 v201, 0x7fffffff, v201
	v_and_b32_e32 v200, 0x7fffffff, v200
	v_and_b32_e32 v203, 0x7fffffff, v203
	v_and_b32_e32 v202, 0x7fffffff, v202
	v_and_b32_e32 v205, 0x7fffffff, v205
	v_and_b32_e32 v204, 0x7fffffff, v204
	v_and_b32_e32 v207, 0x7fffffff, v207
	v_and_b32_e32 v206, 0x7fffffff, v206
	v_and_b32_e32 v208, 0x7fffffff, v130
	v_and_b32_e32 v209, 0x7fffffff, v127
	v_mov_b32_e32 v127, v126
	v_pk_fma_f32 v[78:79], v[126:127], v[206:207], v[78:79]
	v_pk_fma_f32 v[76:77], v[126:127], v[204:205], v[76:77]
	v_pk_fma_f32 v[74:75], v[126:127], v[202:203], v[74:75]
	v_pk_fma_f32 v[72:73], v[126:127], v[200:201], v[72:73]
	v_pk_fma_f32 v[70:71], v[126:127], v[198:199], v[70:71]
	v_pk_fma_f32 v[68:69], v[126:127], v[194:195], v[68:69]
	v_pk_fma_f32 v[66:67], v[126:127], v[192:193], v[66:67]
	v_pk_fma_f32 v[64:65], v[152:153], v[208:209], v[64:65]
	v_pk_add_f32 v[192:193], v[130:131], s[82:83] op_sel_hi:[0,1]
	v_pk_add_f32 v[194:195], v[130:131], s[64:65] op_sel_hi:[0,1]
	v_pk_add_f32 v[198:199], v[130:131], s[60:61] op_sel_hi:[0,1]
	v_pk_add_f32 v[200:201], v[130:131], s[56:57] op_sel_hi:[0,1]
	v_pk_add_f32 v[202:203], v[130:131], s[52:53] op_sel_hi:[0,1]
	v_pk_add_f32 v[204:205], v[130:131], s[48:49] op_sel_hi:[0,1]
	v_pk_add_f32 v[206:207], v[130:131], s[44:45] op_sel_hi:[0,1]
	v_pk_add_f32 v[208:209], v[130:131], s[40:41] op_sel_hi:[0,1]
	v_and_b32_e32 v209, 0x7fffffff, v209
	v_and_b32_e32 v208, 0x7fffffff, v208
	v_and_b32_e32 v207, 0x7fffffff, v207
	v_and_b32_e32 v206, 0x7fffffff, v206
	v_and_b32_e32 v205, 0x7fffffff, v205
	v_and_b32_e32 v204, 0x7fffffff, v204
	v_and_b32_e32 v203, 0x7fffffff, v203
	v_and_b32_e32 v202, 0x7fffffff, v202
	v_and_b32_e32 v201, 0x7fffffff, v201
	v_and_b32_e32 v200, 0x7fffffff, v200
	v_and_b32_e32 v199, 0x7fffffff, v199
	v_and_b32_e32 v198, 0x7fffffff, v198
	v_and_b32_e32 v195, 0x7fffffff, v195
	v_and_b32_e32 v194, 0x7fffffff, v194
	v_and_b32_e32 v193, 0x7fffffff, v193
	v_and_b32_e32 v192, 0x7fffffff, v192
	v_pk_fma_f32 v[94:95], v[126:127], v[192:193], v[94:95]
	v_pk_fma_f32 v[92:93], v[126:127], v[194:195], v[92:93]
	v_pk_fma_f32 v[90:91], v[126:127], v[198:199], v[90:91]
	v_pk_fma_f32 v[88:89], v[126:127], v[200:201], v[88:89]
	v_pk_fma_f32 v[86:87], v[126:127], v[202:203], v[86:87]
	v_pk_fma_f32 v[84:85], v[126:127], v[204:205], v[84:85]
	v_pk_fma_f32 v[82:83], v[126:127], v[206:207], v[82:83]
	v_pk_fma_f32 v[80:81], v[152:153], v[208:209], v[80:81]
.LBB0_591:
	s_nop 9
	v_exp_f32_e32 v127, v64
	v_exp_f32_e32 v130, v80
	v_exp_f32_e32 v191, v65
	v_exp_f32_e32 v194, v81
	v_exp_f32_e32 v195, v66
	v_exp_f32_e32 v197, v82
	v_exp_f32_e32 v198, v67
	v_exp_f32_e32 v199, v83
	v_add_f32_e32 v64, v127, v130
	v_exp_f32_e32 v67, v68
	v_exp_f32_e32 v81, v84
	v_exp_f32_e32 v66, v69
	v_exp_f32_e32 v80, v85
	v_add_f32_e32 v64, 0, v64
	v_add_f32_e32 v65, v191, v194
	v_add_f32_e32 v64, v65, v64
	v_add_f32_e32 v65, v195, v197
	v_add_f32_e32 v64, v65, v64
	v_add_f32_e32 v65, v198, v199
	v_add_f32_e32 v82, v65, v64
	v_pk_add_f32 v[64:65], v[66:67], v[80:81]
	v_exp_f32_e32 v83, v70
	v_add_f32_e32 v65, v65, v82
	v_exp_f32_e32 v85, v86
	v_exp_f32_e32 v82, v71
	v_exp_f32_e32 v84, v87
	v_add_f32_e32 v68, v64, v65
	v_exp_f32_e32 v69, v72
	v_exp_f32_e32 v71, v88
	v_pk_add_f32 v[64:65], v[82:83], v[84:85]
	v_exp_f32_e32 v70, v89
	v_add_f32_e32 v65, v65, v68
	v_exp_f32_e32 v68, v73
	v_add_f32_e32 v86, v64, v65
	v_exp_f32_e32 v87, v74
	v_exp_f32_e32 v89, v90
	v_pk_add_f32 v[64:65], v[68:69], v[70:71]
	v_exp_f32_e32 v88, v91
	v_add_f32_e32 v65, v65, v86
	v_exp_f32_e32 v86, v75
	v_exp_f32_e32 v75, v76
	v_exp_f32_e32 v91, v92
	v_exp_f32_e32 v74, v77
	v_exp_f32_e32 v90, v93
	v_add_f32_e32 v72, v64, v65
	v_pk_add_f32 v[64:65], v[86:87], v[88:89]
	v_exp_f32_e32 v93, v78
	v_exp_f32_e32 v193, v94
	v_exp_f32_e32 v92, v79
	v_exp_f32_e32 v192, v95
	v_add_f32_e32 v65, v65, v72
	v_add_f32_e32 v72, v64, v65
	v_pk_add_f32 v[64:65], v[74:75], v[90:91]
	s_nop 0
	v_add_f32_e32 v65, v65, v72
	v_add_f32_e32 v72, v64, v65
	v_pk_add_f32 v[64:65], v[92:93], v[192:193]
	s_nop 0
	v_add_f32_e32 v65, v65, v72
	v_add_f32_e32 v94, v64, v65
	v_cvt_pk_bf16_f32 v64, v127, v191
	v_cvt_pk_bf16_f32 v68, v69, v68
	v_cvt_pk_bf16_f32 v72, v130, v194
	v_cvt_pk_bf16_f32 v76, v71, v70
	v_cvt_pk_bf16_f32 v65, v195, v198
	v_cvt_pk_bf16_f32 v69, v87, v86
	v_cvt_pk_bf16_f32 v73, v197, v199
	v_cvt_pk_bf16_f32 v77, v89, v88
	v_cvt_pk_bf16_f32 v66, v67, v66
	v_cvt_pk_bf16_f32 v70, v75, v74
	v_cvt_pk_bf16_f32 v74, v81, v80
	v_cvt_pk_bf16_f32 v78, v91, v90
	v_cvt_pk_bf16_f32 v67, v83, v82
	v_cvt_pk_bf16_f32 v71, v93, v92
	v_cvt_pk_bf16_f32 v75, v85, v84
	v_add3_u32 v84, s1, v167, v168
	v_cvt_pk_bf16_f32 v79, v193, v192
	ds_read_b128 v[80:83], v84 offset:16640
	s_waitcnt lgkmcnt(0)
	v_mfma_f32_32x32x16_bf16 v[48:63], v[80:83], v[64:67], v[48:63]
	ds_read_b128 v[80:83], v84 offset:17152
	v_add_f32_e32 v150, v150, v94
	s_waitcnt lgkmcnt(0)
	v_mfma_f32_32x32x16_bf16 v[32:47], v[80:83], v[64:67], v[32:47]
	ds_read_b128 v[80:83], v84 offset:17664
	s_waitcnt lgkmcnt(0)
	v_mfma_f32_32x32x16_bf16 v[16:31], v[80:83], v[64:67], v[16:31]
	ds_read_b128 v[80:83], v84 offset:18176
	s_waitcnt lgkmcnt(0)
	v_mfma_f32_32x32x16_bf16 v[0:15], v[80:83], v[64:67], v[0:15]
	ds_read_b128 v[64:67], v84 offset:20768
	s_waitcnt lgkmcnt(0)
	v_mfma_f32_32x32x16_bf16 v[48:63], v[64:67], v[68:71], v[48:63]
	ds_read_b128 v[64:67], v84 offset:21280
	s_waitcnt lgkmcnt(0)
	v_mfma_f32_32x32x16_bf16 v[32:47], v[64:67], v[68:71], v[32:47]
	ds_read_b128 v[64:67], v84 offset:21792
	s_waitcnt lgkmcnt(0)
	v_mfma_f32_32x32x16_bf16 v[16:31], v[64:67], v[68:71], v[16:31]
	ds_read_b128 v[64:67], v84 offset:22304
	s_waitcnt lgkmcnt(0)
	v_mfma_f32_32x32x16_bf16 v[0:15], v[64:67], v[68:71], v[0:15]
	ds_read_b128 v[64:67], v84 offset:24896
	s_waitcnt lgkmcnt(0)
	v_mfma_f32_32x32x16_bf16 v[48:63], v[64:67], v[72:75], v[48:63]
	ds_read_b128 v[64:67], v84 offset:25408
	s_waitcnt lgkmcnt(0)
	v_mfma_f32_32x32x16_bf16 v[32:47], v[64:67], v[72:75], v[32:47]
	ds_read_b128 v[64:67], v84 offset:25920
	s_waitcnt lgkmcnt(0)
	v_mfma_f32_32x32x16_bf16 v[16:31], v[64:67], v[72:75], v[16:31]
	ds_read_b128 v[64:67], v84 offset:26432
	s_waitcnt lgkmcnt(0)
	v_mfma_f32_32x32x16_bf16 v[0:15], v[64:67], v[72:75], v[0:15]
	ds_read_b128 v[64:67], v84 offset:29024
	s_waitcnt lgkmcnt(0)
	v_mfma_f32_32x32x16_bf16 v[48:63], v[64:67], v[76:79], v[48:63]
	ds_read_b128 v[64:67], v84 offset:29536
	s_waitcnt lgkmcnt(0)
	v_mfma_f32_32x32x16_bf16 v[32:47], v[64:67], v[76:79], v[32:47]
	ds_read_b128 v[64:67], v84 offset:30048
	s_waitcnt lgkmcnt(0)
	v_mfma_f32_32x32x16_bf16 v[16:31], v[64:67], v[76:79], v[16:31]
	ds_read_b128 v[64:67], v84 offset:30560
	s_waitcnt lgkmcnt(0)
	v_mfma_f32_32x32x16_bf16 v[0:15], v[64:67], v[76:79], v[0:15]
.Latt_join:
	s_andn2_b64 vcc, exec, s[10:11]
	s_add_i32 s70, s70, 1
	s_cbranch_vccnz .LBB0_584
.LBB0_592:
	s_bitcmp1_b32 s70, 0
	s_cselect_b32 s1, 0x8200, 0
	s_addk_i32 s1, 0x100
	v_add_u32_e32 v64, s1, v170
	v_add_u32_e32 v65, s1, v172
	s_waitcnt vmcnt(3)
	ds_write_b128 v64, v[96:99]
	s_waitcnt vmcnt(2)
	ds_write_b128 v64, v[100:103] offset:64
	s_waitcnt vmcnt(1)
	ds_write_b128 v65, v[104:107] offset:16640
	s_waitcnt vmcnt(0)
	ds_write_b128 v65, v[108:111] offset:16768
	s_branch .LBB0_584
